# v013 + memory cross-attention prompt units split into 256-token halves (384 units: all 256 workgroups get a prompt half, sample units dealt after)
# speedup vs baseline: 1.0028x; 1.0028x over previous
; #define DEAL_LOOP(F, ctr, N, BODY) do { gu32* _c = (ctr); int u = F.bid; while (u < (N)) { const unsigned _t = deal_prefetch(F, _c); BODY; u = deal_publish(F, _t) + F.G; } __syncthreads(); } while (0)
; #define REPBAR(k) do { if (rep + 1 < REPS(k)) xcd_barrier(bar); } while (0)
; #define LAUNDER() do { launder(F); GAS unsigned char* _g = (GAS unsigned char*)ws; asm volatile("" : "+s"(_g)); ws = (unsigned char*)_g; } while (0)
; __global__ void __launch_bounds__(NTHR, 2) fwd(Args args) {
;     ...
;         if (PH_ON(11) && IN(pb + 10)) for (int rep = 0; rep < REPS(11); ++rep) { LAUNDER(); DEAL_LOOP(F, cnt_word(F, l, CNT_XATTN + 5 * rep), 256, xattn_unit(args, F, l, u)); REPBAR(11); }
.LBB0_2022:
	s_cmp_le_i32 s70, s18
	s_cselect_b64 s[0:1], -1, 0
	s_and_b64 s[2:3], s[0:1], s[2:3]
	s_andn2_b64 vcc, exec, s[2:3]
	s_cbranch_vccnz .LBB0_2045
	v_readlane_b32 s18, v252, 21
	s_cmpk_gt_i32 s69, 0x17f
	v_readlane_b32 s19, v252, 22
	s_cbranch_scc1 .LBB0_2044
	s_lshl_b32 s62, s90, 10
	s_lshl_b64 s[0:1], s[62:63], 2
	s_add_u32 s0, s74, s0
	s_addc_u32 s1, s75, s1
	s_add_u32 s4, s0, 0x10400
	s_addc_u32 s5, s1, 0
	s_lshl_b32 s10, s90, 5
	s_lshl_b32 s11, s90, 19
	v_cmp_eq_u32_e64 s[36:37], 0, v0
	s_lshl_b32 s12, s78, 4
	s_mov_b32 s14, s69
	s_branch .LBB0_2026
.LBB0_2025:
	s_or_b64 exec, exec, s[0:1]
	v_mov_b32_e32 v3, s79
	s_waitcnt lgkmcnt(0)
	s_barrier
	ds_read_b32 v3, v3
	s_waitcnt lgkmcnt(0)
	v_readfirstlane_b32 s0, v3
	s_add_i32 s14, s0, s76
	s_cmpk_lt_i32 s14, 0x180
	s_cbranch_scc0 .LBB0_2044

; DI void xattn_unit(const Args& a, const Frame& F, int l, int unit) {
;     ...
;     const bool prompt = unit < 128;
;     int b, h, row0, nrg;
;     if (prompt) { b = unit >> 5; h = (unit >> 3) & 3; row0 = b * TP + (unit & 7) * 512; nrg = 32; }
;     else { const int u = unit - 128; b = u >> 2; h = u & 3; row0 = NP + b * 64; nrg = 4; }
.LBB0_2030:
	s_or_b64 exec, exec, s[0:1]
	s_cmpk_gt_i32 s14, 0xff
	s_cselect_b64 s[0:1], -1, 0
	v_mov_b32_e32 v95, v160
	s_waitcnt vmcnt(0)
	v_mov_b32_e32 v8, v0
	s_mov_b64 s[6:7], -1
	s_and_b64 vcc, exec, s[0:1]
	s_cbranch_vccz .LBB0_2032
	s_add_i32 s6, s14, 0xffffff00
	s_lshr_b32 s13, s6, 2
	s_lshl_b32 s6, s13, 6
	s_add_i32 s9, s6, 0x4000
	s_mov_b64 s[6:7], 0
.LBB0_2032:
	s_andn2_b64 vcc, exec, s[6:7]
	s_mov_b32 s8, 4
	s_cbranch_vccnz .LBB0_2034
	s_ashr_i32 s13, s14, 6
	s_lshl_b32 s8, s14, 8
	s_lshr_b32 s6, s14, 4
	s_lshl_b32 s7, s13, 12
	s_and_b32 s8, s8, 0xf00
	s_or_b32 s9, s7, s8
	s_mov_b32 s8, 16
	s_mov_b32 s14, s6
